# prologue load balance: rms-norm row loop starts from the mirrored wave index so the 9th row goes to waves that have one weight-conversion item less
# speedup vs baseline: 1.0082x; 1.0082x over previous
.LBB0_236:
	v_readlane_b32 s12, v255, 18
	v_readlane_b32 s13, v255, 19
	s_andn2_b64 vcc, exec, s[12:13]
	s_cbranch_vccnz .LBB0_241
	v_and_b32_e32 v0, 64, v4
	v_add_u32_e32 v0, 64, v0
	v_xor_b32_e32 v1, 1, v4
	v_cmp_lt_i32_e32 vcc, v1, v0
	v_readlane_b32 s66, v255, 30
	v_readlane_b32 s68, v255, 28
	v_cndmask_b32_e32 v1, v4, v1, vcc
	v_lshlrev_b32_e32 v16, 2, v1
	v_xor_b32_e32 v1, 2, v4
	v_cmp_lt_i32_e32 vcc, v1, v0
	v_readlane_b32 s67, v255, 31
	v_readlane_b32 s69, v255, 29
	v_cndmask_b32_e32 v1, v4, v1, vcc
	v_lshlrev_b32_e32 v17, 2, v1
	v_xor_b32_e32 v1, 4, v4
	v_cmp_lt_i32_e32 vcc, v1, v0
	s_nop 1
	v_cndmask_b32_e32 v1, v4, v1, vcc
	v_lshlrev_b32_e32 v18, 2, v1
	v_xor_b32_e32 v1, 8, v4
	v_cmp_lt_i32_e32 vcc, v1, v0
	s_nop 1
	v_cndmask_b32_e32 v1, v4, v1, vcc
	v_lshlrev_b32_e32 v19, 2, v1
	v_xor_b32_e32 v1, 16, v4
	v_cmp_lt_i32_e32 vcc, v1, v0
	s_nop 1
	v_cndmask_b32_e32 v1, v4, v1, vcc
	v_lshlrev_b32_e32 v20, 2, v1
	v_xor_b32_e32 v1, 32, v4
	v_cmp_lt_i32_e32 vcc, v1, v0
	s_nop 1
	v_cndmask_b32_e32 v0, v4, v1, vcc
	v_lshlrev_b32_e32 v21, 2, v0
	s_sub_i32 s12, 0x7ff, s68
	s_sub_i32 s13, s12, s68
	s_mov_b32 s68, s12
	s_mov_b32 s12, s13
	s_ashr_i32 s13, s13, 31
	s_lshl_b64 s[12:13], s[12:13], 12
	s_add_u32 s66, s66, s12
	s_addc_u32 s67, s67, s13
	s_branch .LBB0_239
